# NA-in GEMM unit order 2: the slow transposed-store v units only on workgroups that run 4 units, none on the 64 that run 5
# baseline (speedup 1.0000x reference)
;     __device__ __forceinline__ bool next(int i, Unit& u) const {
;         const int L = i * G + (((i + 1) * G <= n) ? c : cp); if (L >= n) return false;
;         if (mode == 0) { u.pm = L / nN; u.pn = L - u.pm * nN; }
;         else if (mode == 1) {
;             if (L < 544) { const int nn = L / 272, rem = L - nn * 272; u.pm = nn * 68 + (rem >> 2); u.pn = nn * 4 + (rem & 3); }
;             else { const int Lp = L - 544, nn = 2 + Lp / 68; u.pm = nn * 68 + Lp % 68; u.pn = 8 + (nn - 2); }
;         } else if (mode == 4) { const int nn = L / 272, rem = L - nn * 272; u.pm = rem >> 2; u.pn = nn * 4 + (rem & 3); }
;         else if (mode == 3) { const int q = L >> 2; u.pm = (q >> 4) * 17 + (q & 15) + 1; u.pn = L & 3; }
;         else { const int nn = L / 272, rem = L - nn * 272; u.pm = nn * 68 + (rem >> 2); u.pn = nn * 4 + (rem & 3); }
.LBB0_917:
	s_cmp_lt_i32 s34, 10
	s_cselect_b64 s[6:7], -1, 0
	s_cmp_gt_i32 s35, 9
	s_cselect_b64 s[8:9], -1, 0
	s_and_b64 s[6:7], s[6:7], s[8:9]
	s_andn2_b64 vcc, exec, s[6:7]
	s_cbranch_vccnz .LBB0_1000
	s_lshl_b32 s3, s2, 5
	s_and_b32 s3, s3, 0xe0
	s_ashr_i32 s6, s2, 3
	s_add_i32 s3, s3, s6
	s_cmpk_eq_i32 s30, 0x100
	s_cselect_b32 s3, s3, s2
	s_cmpk_gt_i32 s30, 0x440
	s_cselect_b32 s7, s2, s3
	s_cmpk_gt_i32 s7, 0x43f
	s_cbranch_scc1 .Lno2a_end
	s_mov_b32 s95, s7
	s_cmpk_lt_u32 s7, 0x200
	s_cbranch_scc1 .Lno2a_nonv
	s_add_i32 s95, s7, 0xfffffef0
	s_cmpk_gt_u32 s7, 0x3ff
	s_cbranch_scc1 .Lno2a_nonv
	s_and_b32 s93, s7, 31
	s_bfe_u32 s94, s7, 0x30005
	s_cmpk_gt_u32 s7, 0x2ff
	s_cbranch_scc1 .Lno2a_k3
	s_mul_i32 s95, s94, 22
	s_addk_i32 s95, 0x200
	s_cmp_lt_u32 s93, 8
	s_cbranch_scc1 .Lno2a_k2lo
	s_cmp_ge_u32 s93, 18
	s_cbranch_scc1 .Lno2a_k2hi
	s_mul_i32 s95, s94, 10
	s_add_i32 s95, s95, s93
	s_addk_i32 s95, 0xb8
	s_branch .Lno2a_v
.Lno2a_k2hi:
	s_sub_i32 s95, s95, 10
.Lno2a_k2lo:
	s_add_i32 s95, s95, s93
	s_branch .Lno2a_nonv
.Lno2a_k3:
	s_cmp_lt_u32 s93, 8
	s_cbranch_scc1 .Lno2a_k3lo
	s_mul_i32 s95, s94, 24
	s_add_i32 s95, s95, s93
	s_sub_i32 s95, s95, 8
	s_branch .Lno2a_v
.Lno2a_k3lo:
	s_lshl_b32 s95, s94, 3
	s_add_i32 s95, s95, s93
	s_addk_i32 s95, 0x2b0
.Lno2a_nonv:
	s_cmpk_gt_u32 s95, 0x10f
	s_cselect_b32 s94, 1, 0
	s_cmpk_gt_u32 s95, 0x21f
	s_cselect_b32 s93, 1, 0
	s_add_i32 s94, s94, s93
	s_mul_i32 s93, s94, 0x110
	s_sub_i32 s95, s95, s93
	s_lshl_b32 s94, s94, 2
	s_cmp_eq_u32 s94, 8
	s_cselect_b32 s94, 12, s94
	s_branch .Lno2a_fin
.Lno2a_v:
	s_mov_b32 s94, 8
.Lno2a_fin:
	s_lshr_b32 s7, s95, 2
	s_lshl_b32 s7, s7, 4
	s_and_b32 s95, s95, 3
	s_add_i32 s94, s94, s95
	s_add_i32 s7, s7, s94

;     __device__ __forceinline__ bool next(int i, Unit& u) const {
;         const int L = i * G + (((i + 1) * G <= n) ? c : cp); if (L >= n) return false;
;         if (mode == 0) { u.pm = L / nN; u.pn = L - u.pm * nN; }
;         else if (mode == 1) {
;             if (L < 544) { const int nn = L / 272, rem = L - nn * 272; u.pm = nn * 68 + (rem >> 2); u.pn = nn * 4 + (rem & 3); }
;             else { const int Lp = L - 544, nn = 2 + Lp / 68; u.pm = nn * 68 + Lp % 68; u.pn = 8 + (nn - 2); }
;         } else if (mode == 4) { const int nn = L / 272, rem = L - nn * 272; u.pm = rem >> 2; u.pn = nn * 4 + (rem & 3); }
;         else if (mode == 3) { const int q = L >> 2; u.pm = (q >> 4) * 17 + (q & 15) + 1; u.pn = L & 3; }
;         else { const int nn = L / 272, rem = L - nn * 272; u.pm = nn * 68 + (rem >> 2); u.pn = nn * 4 + (rem & 3); }
.LBB0_926:
	s_add_i32 s60, s60, 1
	s_mul_i32 s7, s60, s30
	s_add_i32 s17, s7, s30
	s_cmpk_gt_i32 s17, 0x440
	s_cselect_b32 s17, s2, s3
	s_add_i32 s7, s17, s7
	s_cmpk_gt_i32 s7, 0x43f
	s_cbranch_scc1 .Lno2b_end
	s_mov_b32 s95, s7
	s_cmpk_lt_u32 s7, 0x200
	s_cbranch_scc1 .Lno2b_nonv
	s_add_i32 s95, s7, 0xfffffef0
	s_cmpk_gt_u32 s7, 0x3ff
	s_cbranch_scc1 .Lno2b_nonv
	s_and_b32 s93, s7, 31
	s_bfe_u32 s94, s7, 0x30005
	s_cmpk_gt_u32 s7, 0x2ff
	s_cbranch_scc1 .Lno2b_k3
	s_mul_i32 s95, s94, 22
	s_addk_i32 s95, 0x200
	s_cmp_lt_u32 s93, 8
	s_cbranch_scc1 .Lno2b_k2lo
	s_cmp_ge_u32 s93, 18
	s_cbranch_scc1 .Lno2b_k2hi
	s_mul_i32 s95, s94, 10
	s_add_i32 s95, s95, s93
	s_addk_i32 s95, 0xb8
	s_branch .Lno2b_v
